# INPROJ tile raster changed so each XCD's 64 workgroups cover 8 row panels x 8 weight tiles per step (better L2 sharing); same tiles, same math
# speedup vs baseline: 1.0032x; 1.0032x over previous
; template <class AL, class EPI>
; DI void gemm_wide(const AL& al, const bf16_t* __restrict__ Bt, int K, int m0, int n0, int nhalf, char* smem, const EPI& epi) {
;     ...
; #pragma unroll
;   for (int i = 0; i < 8; ++i) {
;     const int c = tid + 256 * i, row = c >> 3, kc = (c & 7) * 8;
;     if (i < 4) ra[i] = al.load(m0 + row, kc);
;     rb[i] = *(const u32x4*)(Bt + (size_t)(n0 + row) * K + kc);
;   }
; DI void run_phase(const P& p, int ph, int l, int bid, int nblk, char* smem) {
;     ...
;         for (int i = j; i < 64 * 19; i += nj) gemm_wide(al, wl + WO_IN, 1024, (x + 8 * (i / 19)) * 128, (i % 19) * 256, (i % 19) == 18 ? 1 : 2, smem, epi);
.LBB0_600:
	s_lshr_b32 s0, s4, 3
	s_mul_hi_i32 s0, s0, 0x6bca1af3
	s_ashr_i32 s0, s0, 3
	s_mul_i32 s1, s0, 0x98
	s_sub_i32 s1, s4, s1
	s_lshr_b32 s15, s1, 3
	s_and_b32 s1, s1, 7
	s_lshl_b32 s0, s0, 3
	s_add_i32 s0, s0, s1
	s_lshl_b32 s14, s0, 10
	v_readlane_b32 s1, v250, 41
	s_waitcnt vmcnt(2)
	v_mov_b32_e32 v28, v218
	s_or_b32 s1, s14, s1
	v_ashrrev_i32_e32 v29, 3, v28
	s_waitcnt vmcnt(1)
	v_lshlrev_b32_e32 v0, 4, v28
	v_add_u32_e32 v4, s1, v29
	v_and_b32_e32 v192, 0x70, v0
	v_ashrrev_i32_e32 v5, 31, v4
	v_lshl_add_u64 v[2:3], s[92:93], 0, v[192:193]
	v_lshlrev_b64 v[4:5], 11, v[4:5]
	v_writelane_b32 v249, s4, 59
	s_lshl_b32 s12, s15, 8
	v_lshl_add_u64 v[6:7], v[2:3], 0, v[4:5]
	v_readlane_b32 s4, v249, 39
	global_load_dwordx4 v[128:131], v[6:7], off
	v_add_u32_e32 v6, s12, v29
	v_readlane_b32 s5, v249, 40
	v_ashrrev_i32_e32 v7, 31, v6
	v_lshlrev_b64 v[6:7], 11, v[6:7]
	v_lshl_add_u64 v[0:1], s[4:5], 0, v[192:193]
	v_lshl_add_u64 v[8:9], v[0:1], 0, v[6:7]
	global_load_dwordx4 v[132:135], v[8:9], off
	v_add_u32_e32 v8, 0x100, v28
	v_ashrrev_i32_e32 v30, 3, v8
	v_add_u32_e32 v8, s1, v30
	v_ashrrev_i32_e32 v9, 31, v8
	v_lshlrev_b64 v[8:9], 11, v[8:9]
	v_lshl_add_u64 v[10:11], v[2:3], 0, v[8:9]
	global_load_dwordx4 v[136:139], v[10:11], off
	v_add_u32_e32 v10, s12, v30
	v_ashrrev_i32_e32 v11, 31, v10
	v_lshlrev_b64 v[10:11], 11, v[10:11]
	v_lshl_add_u64 v[12:13], v[0:1], 0, v[10:11]
	global_load_dwordx4 v[140:143], v[12:13], off
	v_add_u32_e32 v12, 0x200, v28
	v_ashrrev_i32_e32 v31, 3, v12
	v_add_u32_e32 v12, s1, v31
	v_ashrrev_i32_e32 v13, 31, v12
	v_lshlrev_b64 v[12:13], 11, v[12:13]
	v_lshl_add_u64 v[14:15], v[2:3], 0, v[12:13]
	global_load_dwordx4 v[144:147], v[14:15], off
	v_add_u32_e32 v14, s12, v31
	v_ashrrev_i32_e32 v15, 31, v14
	v_lshlrev_b64 v[14:15], 11, v[14:15]
	v_lshl_add_u64 v[16:17], v[0:1], 0, v[14:15]
	global_load_dwordx4 v[148:151], v[16:17], off
	v_add_u32_e32 v16, 0x300, v28
	s_waitcnt lgkmcnt(14)
	v_ashrrev_i32_e32 v32, 3, v16
	v_add_u32_e32 v16, s1, v32
	v_ashrrev_i32_e32 v17, 31, v16
	v_lshlrev_b64 v[16:17], 11, v[16:17]
	v_lshl_add_u64 v[2:3], v[2:3], 0, v[16:17]
	s_waitcnt vmcnt(6)
	v_add_u32_e32 v20, 0x400, v28
	global_load_dwordx4 v[152:155], v[2:3], off
	v_add_u32_e32 v2, s12, v32
	v_ashrrev_i32_e32 v33, 3, v20
	v_ashrrev_i32_e32 v3, 31, v2
	v_add_u32_e32 v20, s12, v33
	v_lshlrev_b64 v[2:3], 11, v[2:3]
	v_ashrrev_i32_e32 v21, 31, v20
	v_lshl_add_u64 v[18:19], v[0:1], 0, v[2:3]
	v_lshlrev_b64 v[20:21], 11, v[20:21]
	s_waitcnt lgkmcnt(0)
; template <class AL, class EPI>
; DI void gemm_wide(const AL& al, const bf16_t* __restrict__ Bt, int K, int m0, int n0, int nhalf, char* smem, const EPI& epi) {
;     ...
;   f32x16 acc[2][4];
; #pragma unroll
;   for (int i = 0; i < 2; ++i)
; #pragma unroll
;     for (int j = 0; j < 4; ++j)
; #pragma unroll
;       for (int r = 0; r < 16; ++r) acc[i][j][r] = 0.f;
;   u32x4 ra[4], rb[8];
;   const int nkt = K >> 6;
; #pragma unroll
;   for (int i = 0; i < 8; ++i) {
;     const int c = tid + 256 * i, row = c >> 3, kc = (c & 7) * 8;
;     if (i < 4) ra[i] = al.load(m0 + row, kc);
;     rb[i] = *(const u32x4*)(Bt + (size_t)(n0 + row) * K + kc);
;   }
	v_lshl_add_u64 v[22:23], v[0:1], 0, v[20:21]
	global_load_dwordx4 v[156:159], v[18:19], off
	global_load_dwordx4 v[160:163], v[22:23], off
	v_add_u32_e32 v18, 0x500, v28
	v_ashrrev_i32_e32 v34, 3, v18
	v_add_u32_e32 v24, 0x600, v28
	v_add_u32_e32 v18, s12, v34
	v_ashrrev_i32_e32 v35, 3, v24
	v_ashrrev_i32_e32 v19, 31, v18
	v_add_u32_e32 v24, s12, v35
	v_lshlrev_b64 v[18:19], 11, v[18:19]
	v_ashrrev_i32_e32 v25, 31, v24
	v_lshl_add_u64 v[22:23], v[0:1], 0, v[18:19]
	v_lshlrev_b64 v[24:25], 11, v[24:25]
	v_lshl_add_u64 v[26:27], v[0:1], 0, v[24:25]
	global_load_dwordx4 v[164:167], v[22:23], off
	global_load_dwordx4 v[168:171], v[26:27], off
	v_add_u32_e32 v22, 0x700, v28
	v_ashrrev_i32_e32 v26, 3, v22
	v_add_u32_e32 v22, s12, v26
	v_ashrrev_i32_e32 v23, 31, v22
	v_lshlrev_b64 v[22:23], 11, v[22:23]
	v_lshl_add_u64 v[0:1], v[0:1], 0, v[22:23]
	global_load_dwordx4 v[172:175], v[0:1], off
	v_ashrrev_i32_e32 v0, 1, v28
	v_readlane_b32 s0, v250, 63
	v_bfe_u32 v210, v28, 6, 1
	v_and_b32_e32 v211, 31, v28
	v_and_b32_e32 v212, 0xffffffc0, v0
	v_or_b32_e32 v4, v4, v192
	v_readlane_b32 s1, v249, 0
	v_or_b32_e32 v8, v8, v192
	v_or_b32_e32 v12, v12, v192
	v_or_b32_e32 v16, v16, v192
	v_bfe_u32 v213, v28, 5, 1
	v_or_b32_e32 v0, v212, v211
	v_lshl_or_b32 v28, v210, 7, v211
	v_lshl_add_u64 v[184:185], s[0:1], 0, v[4:5]
	v_lshl_add_u64 v[186:187], s[0:1], 0, v[8:9]
	v_lshl_add_u64 v[188:189], s[0:1], 0, v[12:13]
	v_lshl_add_u64 v[190:191], s[0:1], 0, v[16:17]
	v_readlane_b32 s0, v249, 54
	v_add_u32_e32 v1, 0, v192
	v_lshl_add_u32 v27, v213, 4, 0
	v_mul_lo_u32 v29, v29, s33
	v_mul_lo_u32 v30, v30, s33
	v_mul_lo_u32 v31, v31, s33
	v_mul_lo_u32 v32, v32, s33
	v_mul_lo_u32 v33, v33, s33
	v_mul_lo_u32 v34, v34, s33
	v_mul_lo_u32 v35, v35, s33
	v_mul_lo_u32 v26, v26, s33
	v_mul_lo_u32 v36, v0, s33
	v_mul_u32_u24_e32 v28, 0x90, v28
	v_or_b32_e32 v6, v6, v192
	v_readlane_b32 s1, v249, 55
	v_or_b32_e32 v10, v10, v192
	v_or_b32_e32 v14, v14, v192
	v_or_b32_e32 v2, v2, v192
	v_or_b32_e32 v20, v20, v192
	v_or_b32_e32 v18, v18, v192
	v_or_b32_e32 v24, v24, v192
	v_or_b32_e32 v22, v22, v192
	v_mov_b32_e32 v0, 0
	v_lshl_add_u64 v[194:195], s[0:1], 0, v[6:7]
	v_lshl_add_u64 v[196:197], s[0:1], 0, v[10:11]
	v_lshl_add_u64 v[198:199], s[0:1], 0, v[14:15]
	v_lshl_add_u64 v[200:201], s[0:1], 0, v[2:3]
	v_lshl_add_u64 v[202:203], s[0:1], 0, v[20:21]
	v_lshl_add_u64 v[204:205], s[0:1], 0, v[18:19]
	v_lshl_add_u64 v[206:207], s[0:1], 0, v[24:25]
	v_lshl_add_u64 v[208:209], s[0:1], 0, v[22:23]
	s_mov_b64 s[0:1], 0
	v_add_u32_e32 v192, v1, v29
	v_add_u32_e32 v214, v1, v30
	v_add_u32_e32 v215, v1, v31
	v_add_u32_e32 v216, v1, v32
	v_add_u32_e32 v217, v1, v33
	v_add_u32_e32 v227, v1, v34
	v_add_u32_e32 v228, v1, v35
	v_add_u32_e32 v229, v1, v26
	v_add_u32_e32 v230, v27, v36
	v_add_u32_e32 v231, v27, v28
	v_mov_b32_e32 v1, v0
	v_mov_b32_e32 v2, v0
	v_mov_b32_e32 v3, v0
	v_mov_b32_e32 v4, v0
	v_mov_b32_e32 v5, v0
	v_mov_b32_e32 v6, v0
	v_mov_b32_e32 v7, v0
	v_mov_b32_e32 v8, v0
	v_mov_b32_e32 v9, v0
	v_mov_b32_e32 v10, v0
	v_mov_b32_e32 v11, v0
	v_mov_b32_e32 v12, v0
	v_mov_b32_e32 v13, v0
	v_mov_b32_e32 v14, v0
	v_mov_b32_e32 v15, v0
	v_mov_b32_e32 v16, v0
	v_mov_b32_e32 v17, v0
	v_mov_b32_e32 v18, v0
	v_mov_b32_e32 v19, v0
	v_mov_b32_e32 v20, v0
	v_mov_b32_e32 v21, v0
	v_mov_b32_e32 v22, v0
	v_mov_b32_e32 v23, v0
	v_mov_b32_e32 v24, v0
	v_mov_b32_e32 v25, v0
	v_mov_b32_e32 v26, v0
	v_mov_b32_e32 v27, v0
	v_mov_b32_e32 v28, v0
	v_mov_b32_e32 v29, v0
	v_mov_b32_e32 v30, v0
	v_mov_b32_e32 v31, v0
	v_mov_b32_e32 v32, v0
	v_mov_b32_e32 v33, v0
	v_mov_b32_e32 v34, v0
	v_mov_b32_e32 v35, v0
	v_mov_b32_e32 v36, v0
	v_mov_b32_e32 v37, v0
	v_mov_b32_e32 v38, v0
	v_mov_b32_e32 v39, v0
	v_mov_b32_e32 v40, v0
	v_mov_b32_e32 v41, v0
	v_mov_b32_e32 v42, v0
	v_mov_b32_e32 v43, v0
	v_mov_b32_e32 v44, v0
	v_mov_b32_e32 v45, v0
	v_mov_b32_e32 v46, v0
	v_mov_b32_e32 v47, v0
	v_mov_b32_e32 v48, v0
	v_mov_b32_e32 v49, v0
	v_mov_b32_e32 v50, v0
	v_mov_b32_e32 v51, v0
	v_mov_b32_e32 v52, v0
	v_mov_b32_e32 v53, v0
	v_mov_b32_e32 v54, v0
	v_mov_b32_e32 v55, v0
	v_mov_b32_e32 v56, v0
	v_mov_b32_e32 v57, v0
	v_mov_b32_e32 v58, v0
	v_mov_b32_e32 v59, v0
	v_mov_b32_e32 v60, v0
	v_mov_b32_e32 v61, v0
	v_mov_b32_e32 v62, v0
	v_mov_b32_e32 v63, v0
	v_mov_b32_e32 v64, v0
	v_mov_b32_e32 v65, v0
	v_mov_b32_e32 v66, v0
	v_mov_b32_e32 v67, v0
	v_mov_b32_e32 v68, v0
	v_mov_b32_e32 v69, v0
	v_mov_b32_e32 v70, v0
	v_mov_b32_e32 v71, v0
	v_mov_b32_e32 v72, v0
	v_mov_b32_e32 v73, v0
	v_mov_b32_e32 v74, v0
	v_mov_b32_e32 v75, v0
	v_mov_b32_e32 v76, v0
	v_mov_b32_e32 v77, v0
	v_mov_b32_e32 v78, v0
	v_mov_b32_e32 v79, v0
	v_mov_b32_e32 v80, v0
	v_mov_b32_e32 v81, v0
	v_mov_b32_e32 v82, v0
	v_mov_b32_e32 v83, v0
	v_mov_b32_e32 v84, v0
	v_mov_b32_e32 v85, v0
	v_mov_b32_e32 v86, v0
	v_mov_b32_e32 v87, v0
	v_mov_b32_e32 v88, v0
	v_mov_b32_e32 v89, v0
	v_mov_b32_e32 v90, v0
	v_mov_b32_e32 v91, v0
	v_mov_b32_e32 v92, v0
	v_mov_b32_e32 v93, v0
	v_mov_b32_e32 v94, v0
	v_mov_b32_e32 v95, v0
	v_mov_b32_e32 v96, v0
	v_mov_b32_e32 v97, v0
	v_mov_b32_e32 v98, v0
	v_mov_b32_e32 v99, v0
	v_mov_b32_e32 v100, v0
	v_mov_b32_e32 v101, v0
	v_mov_b32_e32 v102, v0
	v_mov_b32_e32 v103, v0
	v_mov_b32_e32 v104, v0
	v_mov_b32_e32 v105, v0
	v_mov_b32_e32 v106, v0
	v_mov_b32_e32 v107, v0
	v_mov_b32_e32 v108, v0
	v_mov_b32_e32 v109, v0
	v_mov_b32_e32 v110, v0
	v_mov_b32_e32 v111, v0
	v_mov_b32_e32 v112, v0
	v_mov_b32_e32 v113, v0
	v_mov_b32_e32 v114, v0
	v_mov_b32_e32 v115, v0
	v_mov_b32_e32 v116, v0
	v_mov_b32_e32 v117, v0
	v_mov_b32_e32 v118, v0
	v_mov_b32_e32 v119, v0
	v_mov_b32_e32 v120, v0
	v_mov_b32_e32 v121, v0
	v_mov_b32_e32 v122, v0
	v_mov_b32_e32 v123, v0
	v_mov_b32_e32 v124, v0
	v_mov_b32_e32 v125, v0
	v_mov_b32_e32 v126, v0
	v_mov_b32_e32 v127, v0
	s_branch .LBB0_602
